# counted-wait relocation in the weight-conversion loops of P0 and the P1/P15/P17 tails: hipcc's vmcnt waits between the prefetch loads and the convert+store block moved in front of the register copies;
# baseline (speedup 1.0000x reference)
.LBB0_273:
	s_mov_b32 s56, 0
	s_mov_b32 s53, s38
	s_waitcnt vmcnt(0)
	s_branch .LBB0_275
.LBB0_274:
	s_waitcnt vmcnt(0)
	s_andn2_b64 vcc, exec, s[54:55]
	s_mov_b64 s[30:31], s[50:51]
	s_mov_b32 s4, s57
	s_mov_b32 s36, s62
	s_mov_b32 s46, s58
	v_mov_b32_e32 v90, v59
	v_mov_b32_e32 v2, v54
	v_mov_b32_e32 v78, v55
	v_mov_b32_e32 v4, v56
	v_mov_b32_e32 v70, v57
	v_mov_b32_e32 v58, v50
	v_mov_b32_e32 v79, v51
	v_mov_b32_e32 v5, v52
	v_mov_b32_e32 v71, v53
	v_mov_b32_e32 v6, v42
	v_mov_b32_e32 v80, v43
	v_mov_b32_e32 v8, v44
	v_mov_b32_e32 v72, v45
	v_mov_b32_e32 v7, v38
	v_mov_b32_e32 v81, v39
	v_mov_b32_e32 v9, v40
	v_mov_b32_e32 v73, v41
	v_mov_b32_e32 v10, v34
	v_mov_b32_e32 v82, v35
	v_mov_b32_e32 v12, v36
	v_mov_b32_e32 v74, v37
	v_mov_b32_e32 v11, v30
	v_mov_b32_e32 v83, v31
	v_mov_b32_e32 v13, v32
	v_mov_b32_e32 v75, v33
	v_mov_b32_e32 v14, v22
	v_mov_b32_e32 v84, v23
	v_mov_b32_e32 v16, v24
	v_mov_b32_e32 v76, v25
	s_waitcnt vmcnt(0)
	v_mov_b32_e32 v15, v46
	v_mov_b32_e32 v85, v47
	v_mov_b32_e32 v17, v48
	v_mov_b32_e32 v77, v49
	v_mov_b32_e32 v26, v60
	v_mov_b32_e32 v27, v61
	v_mov_b32_e32 v28, v62
	v_mov_b32_e32 v29, v63
	v_mov_b32_e32 v18, v64
	v_mov_b32_e32 v19, v65
	v_mov_b32_e32 v20, v66
	v_mov_b32_e32 v21, v67
	s_cbranch_vccz .LBB0_256

.LBB0_292:
	v_mov_b32_e32 v63, v91
	v_mov_b32_e32 v62, v91
	v_mov_b32_e32 v61, v91
	v_mov_b32_e32 v60, v91
	v_mov_b32_e32 v67, v91
	v_mov_b32_e32 v66, v91
	v_mov_b32_e32 v65, v91
	v_mov_b32_e32 v64, v91
.LBB0_293:
	v_mul_f32_e32 v92, v2, v26
	v_add_u32_e32 v2, s36, v1
	v_ashrrev_i32_e32 v93, 31, v2
	v_mad_u64_u32 v[2:3], s[36:37], v2, s4, 0
	v_mov_b32_e32 v94, v3
	v_cmp_nlt_f32_e32 vcc, 0, v90
	v_mad_u64_u32 v[94:95], s[36:37], v93, s4, v[94:95]
	v_mov_b32_e32 v3, v94
	s_ashr_i32 s47, s46, 31
	s_mov_b64 s[36:37], -1
	v_mul_f32_e32 v58, v58, v27
	s_cbranch_vccz .LBB0_295
	v_lshl_add_u64 v[94:95], v[2:3], 1, s[30:31]
	v_lshl_add_u64 v[94:95], s[46:47], 1, v[94:95]
	v_lshlrev_b32_e32 v96, 1, v164
	v_mov_b32_e32 v97, v69
	v_lshl_add_u64 v[98:99], v[94:95], 0, v[96:97]
	v_pk_mul_f32 v[96:97], v[6:7], v[28:29]
	v_pk_mul_f32 v[100:101], v[14:15], v[20:21]
	v_cvt_pk_bf16_f32 v95, v96, v97
	v_pk_mul_f32 v[96:97], v[10:11], v[18:19]
	v_cvt_pk_bf16_f32 v94, v92, v58
	v_cvt_pk_bf16_f32 v96, v96, v97
	v_cvt_pk_bf16_f32 v97, v100, v101
	global_store_dwordx4 v[98:99], v[94:97], off
	v_pk_mul_f32 v[100:101], v[84:85], v[20:21]
	s_lshl_b64 s[36:37], s[4:5], 1
	v_pk_mul_f32 v[94:95], v[78:79], v[26:27]
	v_pk_mul_f32 v[96:97], v[80:81], v[28:29]
	v_cvt_pk_bf16_f32 v94, v94, v95
	v_cvt_pk_bf16_f32 v95, v96, v97
	v_pk_mul_f32 v[96:97], v[82:83], v[18:19]
	v_lshl_add_u64 v[98:99], v[98:99], 0, s[36:37]
	v_cvt_pk_bf16_f32 v96, v96, v97
	v_cvt_pk_bf16_f32 v97, v100, v101
	global_store_dwordx4 v[98:99], v[94:97], off
	v_pk_mul_f32 v[100:101], v[16:17], v[20:21]
	v_lshl_add_u64 v[98:99], v[98:99], 0, s[36:37]
	v_pk_mul_f32 v[94:95], v[4:5], v[26:27]
	v_pk_mul_f32 v[96:97], v[8:9], v[28:29]
	v_cvt_pk_bf16_f32 v94, v94, v95
	v_cvt_pk_bf16_f32 v95, v96, v97
	v_pk_mul_f32 v[96:97], v[12:13], v[18:19]
	s_nop 0
	v_cvt_pk_bf16_f32 v96, v96, v97
	v_cvt_pk_bf16_f32 v97, v100, v101
	global_store_dwordx4 v[98:99], v[94:97], off
	v_pk_mul_f32 v[100:101], v[76:77], v[20:21]
	v_lshl_add_u64 v[98:99], v[98:99], 0, s[36:37]
	v_pk_mul_f32 v[94:95], v[70:71], v[26:27]
	v_pk_mul_f32 v[96:97], v[72:73], v[28:29]
	v_cvt_pk_bf16_f32 v94, v94, v95
	v_cvt_pk_bf16_f32 v95, v96, v97
	v_pk_mul_f32 v[96:97], v[74:75], v[18:19]
	s_mov_b64 s[36:37], 0
	v_cvt_pk_bf16_f32 v96, v96, v97
	v_cvt_pk_bf16_f32 v97, v100, v101
	global_store_dwordx4 v[98:99], v[94:97], off
.LBB0_295:
	s_andn2_b64 vcc, exec, s[36:37]
	s_cbranch_vccnz .LBB0_274
	v_mul_f32_e32 v92, v92, v90
	v_mul_f32_e32 v58, v58, v90
	v_mul_f32_e32 v6, v6, v28
	v_mul_f32_e32 v93, v6, v90
	v_med3_f32 v92, v92, s26, v89
	v_med3_f32 v58, v58, s26, v89
	v_mov_b32_e32 v6, v69
	v_cvt_pk_fp8_f32 v6, v92, v58
	v_mul_f32_e32 v7, v7, v29
	v_mul_f32_e32 v7, v7, v90
	v_med3_f32 v58, v93, s26, v89
	v_med3_f32 v7, v7, s26, v89
	v_cvt_pk_fp8_f32 v6, v58, v7 op_sel:[0,0,1]
	v_mul_f32_e32 v7, v10, v18
	v_mul_f32_e32 v10, v11, v19
	v_mul_f32_e32 v7, v7, v90
	v_mul_f32_e32 v10, v10, v90
	v_mul_f32_e32 v11, v14, v20
	v_mul_f32_e32 v14, v15, v21
	v_med3_f32 v15, v7, s26, v89
	v_med3_f32 v10, v10, s26, v89
	v_mov_b32_e32 v7, v69
	v_cvt_pk_fp8_f32 v7, v15, v10
	v_mul_f32_e32 v11, v11, v90
	v_mul_f32_e32 v10, v14, v90
	v_med3_f32 v11, v11, s26, v89
	v_med3_f32 v10, v10, s26, v89
	v_cvt_pk_fp8_f32 v7, v11, v10 op_sel:[0,0,1]
	v_mul_f32_e32 v10, v78, v26
	v_mul_f32_e32 v11, v79, v27
	v_lshl_add_u64 v[2:3], s[30:31], 0, v[2:3]
	v_mul_f32_e32 v10, v10, v90
	v_mul_f32_e32 v11, v11, v90
	v_lshl_add_u64 v[2:3], v[2:3], 0, s[46:47]
	v_med3_f32 v58, v10, s26, v89
	v_med3_f32 v11, v11, s26, v89
	v_mov_b32_e32 v10, v69
	v_mul_f32_e32 v4, v4, v26
	v_mul_f32_e32 v5, v5, v27
	v_cvt_pk_fp8_f32 v10, v58, v11
	v_lshl_add_u64 v[2:3], v[2:3], 0, v[164:165]
	v_mul_f32_e32 v4, v4, v90
	v_mul_f32_e32 v5, v5, v90
	v_mul_f32_e32 v14, v80, v28
	v_mul_f32_e32 v15, v81, v29
	global_store_dwordx2 v[2:3], v[6:7], off
	v_mul_f32_e32 v6, v8, v28
	v_med3_f32 v8, v4, s26, v89
	v_med3_f32 v5, v5, s26, v89
	v_mov_b32_e32 v4, v69
	v_mul_f32_e32 v14, v14, v90
	v_mul_f32_e32 v11, v15, v90
	v_cvt_pk_fp8_f32 v4, v8, v5
	v_med3_f32 v14, v14, s26, v89
	v_med3_f32 v11, v11, s26, v89
	v_mul_f32_e32 v7, v9, v29
	v_cvt_pk_fp8_f32 v10, v14, v11 op_sel:[0,0,1]
	v_mul_f32_e32 v11, v82, v18
	v_mul_f32_e32 v14, v83, v19
	v_mul_f32_e32 v6, v6, v90
	v_mul_f32_e32 v5, v7, v90
	v_mul_f32_e32 v11, v11, v90
	v_mul_f32_e32 v14, v14, v90
	v_med3_f32 v6, v6, s26, v89
	v_med3_f32 v5, v5, s26, v89
	v_med3_f32 v78, v11, s26, v89
	v_med3_f32 v14, v14, s26, v89
	v_mov_b32_e32 v11, v69
	v_cvt_pk_fp8_f32 v4, v6, v5 op_sel:[0,0,1]
	v_mul_f32_e32 v5, v12, v18
	v_mul_f32_e32 v6, v13, v19
	v_cvt_pk_fp8_f32 v11, v78, v14
	v_mul_f32_e32 v5, v5, v90
	v_mul_f32_e32 v6, v6, v90
	v_mul_f32_e32 v15, v84, v20
	v_mul_f32_e32 v58, v85, v21
	v_med3_f32 v9, v5, s26, v89
	v_med3_f32 v6, v6, s26, v89
	v_mov_b32_e32 v5, v69
	v_mul_f32_e32 v15, v15, v90
	v_mul_f32_e32 v14, v58, v90
	v_cvt_pk_fp8_f32 v5, v9, v6
	v_med3_f32 v15, v15, s26, v89
	v_med3_f32 v14, v14, s26, v89
	v_mul_f32_e32 v7, v16, v20
	v_mul_f32_e32 v8, v17, v21
	v_cvt_pk_fp8_f32 v11, v15, v14 op_sel:[0,0,1]
	v_mul_f32_e32 v7, v7, v90
	v_mul_f32_e32 v6, v8, v90
	v_med3_f32 v7, v7, s26, v89
	v_med3_f32 v6, v6, s26, v89
	v_cvt_pk_fp8_f32 v5, v7, v6 op_sel:[0,0,1]
	v_mul_f32_e32 v6, v70, v26
	v_mul_f32_e32 v7, v71, v27
	v_lshl_add_u64 v[2:3], v[2:3], 0, s[4:5]
	v_mul_f32_e32 v6, v6, v90
	v_mul_f32_e32 v7, v7, v90
	global_store_dwordx2 v[2:3], v[10:11], off
	v_med3_f32 v10, v6, s26, v89
	v_med3_f32 v7, v7, s26, v89
	v_mov_b32_e32 v6, v69
	v_cvt_pk_fp8_f32 v6, v10, v7
	v_mul_f32_e32 v8, v72, v28
	v_mul_f32_e32 v9, v73, v29
	v_mul_f32_e32 v8, v8, v90
	v_mul_f32_e32 v7, v9, v90
	v_med3_f32 v8, v8, s26, v89
	v_med3_f32 v7, v7, s26, v89
	v_cvt_pk_fp8_f32 v6, v8, v7 op_sel:[0,0,1]
	v_mul_f32_e32 v7, v74, v18
	v_mul_f32_e32 v8, v75, v19
	v_mul_f32_e32 v7, v7, v90
	v_mul_f32_e32 v8, v8, v90
	v_med3_f32 v11, v7, s26, v89
	v_med3_f32 v8, v8, s26, v89
	v_mov_b32_e32 v7, v69
	v_cvt_pk_fp8_f32 v7, v11, v8
	v_mul_f32_e32 v9, v76, v20
	v_mul_f32_e32 v10, v77, v21
	v_mul_f32_e32 v9, v9, v90
	v_mul_f32_e32 v8, v10, v90
	v_med3_f32 v9, v9, s26, v89
	v_med3_f32 v8, v8, s26, v89
	v_cvt_pk_fp8_f32 v7, v9, v8 op_sel:[0,0,1]
	v_lshl_add_u64 v[2:3], v[2:3], 0, s[4:5]
	global_store_dwordx2 v[2:3], v[4:5], off
	v_lshl_add_u64 v[2:3], v[2:3], 0, s[4:5]
	global_store_dwordx2 v[2:3], v[6:7], off
	s_branch .LBB0_274

.LBB0_1982:
	s_mov_b32 s68, 0
	s_mov_b32 s67, s64
	s_waitcnt vmcnt(0)
	s_branch .LBB0_1984
.LBB0_1983:
	s_waitcnt vmcnt(0)
	s_andn2_b64 vcc, exec, s[56:57]
	s_mov_b64 s[24:25], s[54:55]
	s_mov_b32 s4, s33
	s_mov_b32 s14, s66
	s_mov_b32 s52, s58
	v_mov_b32_e32 v90, v59
	v_mov_b32_e32 v2, v54
	v_mov_b32_e32 v78, v55
	v_mov_b32_e32 v4, v56
	v_mov_b32_e32 v70, v57
	v_mov_b32_e32 v58, v50
	v_mov_b32_e32 v79, v51
	v_mov_b32_e32 v5, v52
	v_mov_b32_e32 v71, v53
	v_mov_b32_e32 v6, v42
	v_mov_b32_e32 v80, v43
	v_mov_b32_e32 v8, v44
	v_mov_b32_e32 v72, v45
	v_mov_b32_e32 v7, v38
	v_mov_b32_e32 v81, v39
	v_mov_b32_e32 v9, v40
	v_mov_b32_e32 v73, v41
	v_mov_b32_e32 v10, v34
	v_mov_b32_e32 v82, v35
	v_mov_b32_e32 v12, v36
	v_mov_b32_e32 v74, v37
	v_mov_b32_e32 v11, v30
	v_mov_b32_e32 v83, v31
	v_mov_b32_e32 v13, v32
	v_mov_b32_e32 v75, v33
	v_mov_b32_e32 v14, v22
	v_mov_b32_e32 v84, v23
	v_mov_b32_e32 v16, v24
	v_mov_b32_e32 v76, v25
	s_waitcnt vmcnt(0)
	v_mov_b32_e32 v15, v46
	v_mov_b32_e32 v85, v47
	v_mov_b32_e32 v17, v48
	v_mov_b32_e32 v77, v49
	v_mov_b32_e32 v26, v60
	v_mov_b32_e32 v27, v61
	v_mov_b32_e32 v28, v62
	v_mov_b32_e32 v29, v63
	v_mov_b32_e32 v18, v64
	v_mov_b32_e32 v19, v65
	v_mov_b32_e32 v20, v66
	v_mov_b32_e32 v21, v67
	s_cbranch_vccz .LBB0_1958

.LBB0_2048:
	v_mul_f32_e32 v92, v2, v26
	v_add_u32_e32 v2, s14, v1
	v_ashrrev_i32_e32 v93, 31, v2
	v_mad_u64_u32 v[2:3], s[36:37], v2, s4, 0
	v_mov_b32_e32 v94, v3
	v_cmp_nlt_f32_e32 vcc, 0, v90
	v_mad_u64_u32 v[94:95], s[36:37], v93, s4, v[94:95]
	v_mov_b32_e32 v3, v94
	s_ashr_i32 s53, s52, 31
	s_mov_b64 s[36:37], -1
	v_mul_f32_e32 v58, v58, v27
	s_cbranch_vccz .LBB0_2050
	v_lshl_add_u64 v[94:95], v[2:3], 1, s[24:25]
	v_lshl_add_u64 v[94:95], s[52:53], 1, v[94:95]
	v_lshlrev_b32_e32 v96, 1, v164
	v_mov_b32_e32 v97, v69
	v_lshl_add_u64 v[98:99], v[94:95], 0, v[96:97]
	v_pk_mul_f32 v[96:97], v[6:7], v[28:29]
	v_pk_mul_f32 v[100:101], v[14:15], v[20:21]
	v_cvt_pk_bf16_f32 v95, v96, v97
	v_pk_mul_f32 v[96:97], v[10:11], v[18:19]
	v_cvt_pk_bf16_f32 v94, v92, v58
	v_cvt_pk_bf16_f32 v96, v96, v97
	v_cvt_pk_bf16_f32 v97, v100, v101
	global_store_dwordx4 v[98:99], v[94:97], off
	v_pk_mul_f32 v[100:101], v[84:85], v[20:21]
	s_lshl_b64 s[36:37], s[4:5], 1
	v_pk_mul_f32 v[94:95], v[78:79], v[26:27]
	v_pk_mul_f32 v[96:97], v[80:81], v[28:29]
	v_cvt_pk_bf16_f32 v94, v94, v95
	v_cvt_pk_bf16_f32 v95, v96, v97
	v_pk_mul_f32 v[96:97], v[82:83], v[18:19]
	v_lshl_add_u64 v[98:99], v[98:99], 0, s[36:37]
	v_cvt_pk_bf16_f32 v96, v96, v97
	v_cvt_pk_bf16_f32 v97, v100, v101
	global_store_dwordx4 v[98:99], v[94:97], off
	v_pk_mul_f32 v[100:101], v[16:17], v[20:21]
	v_lshl_add_u64 v[98:99], v[98:99], 0, s[36:37]
	v_pk_mul_f32 v[94:95], v[4:5], v[26:27]
	v_pk_mul_f32 v[96:97], v[8:9], v[28:29]
	v_cvt_pk_bf16_f32 v94, v94, v95
	v_cvt_pk_bf16_f32 v95, v96, v97
	v_pk_mul_f32 v[96:97], v[12:13], v[18:19]
	s_nop 0
	v_cvt_pk_bf16_f32 v96, v96, v97
	v_cvt_pk_bf16_f32 v97, v100, v101
	global_store_dwordx4 v[98:99], v[94:97], off
	v_pk_mul_f32 v[100:101], v[76:77], v[20:21]
	v_lshl_add_u64 v[98:99], v[98:99], 0, s[36:37]
	v_pk_mul_f32 v[94:95], v[70:71], v[26:27]
	v_pk_mul_f32 v[96:97], v[72:73], v[28:29]
	v_cvt_pk_bf16_f32 v94, v94, v95
	v_cvt_pk_bf16_f32 v95, v96, v97
	v_pk_mul_f32 v[96:97], v[74:75], v[18:19]
	s_mov_b64 s[36:37], 0
	v_cvt_pk_bf16_f32 v96, v96, v97
	v_cvt_pk_bf16_f32 v97, v100, v101
	global_store_dwordx4 v[98:99], v[94:97], off
.LBB0_2050:
	s_andn2_b64 vcc, exec, s[36:37]
	s_cbranch_vccnz .LBB0_1983
	v_mul_f32_e32 v92, v92, v90
	v_mul_f32_e32 v58, v58, v90
	v_mul_f32_e32 v6, v6, v28
	v_mul_f32_e32 v93, v6, v90
	v_med3_f32 v92, v92, s62, v89
	v_med3_f32 v58, v58, s62, v89
	v_mov_b32_e32 v6, v69
	v_cvt_pk_fp8_f32 v6, v92, v58
	v_mul_f32_e32 v7, v7, v29
	v_mul_f32_e32 v7, v7, v90
	v_med3_f32 v58, v93, s62, v89
	v_med3_f32 v7, v7, s62, v89
	v_cvt_pk_fp8_f32 v6, v58, v7 op_sel:[0,0,1]
	v_mul_f32_e32 v7, v10, v18
	v_mul_f32_e32 v10, v11, v19
	v_mul_f32_e32 v7, v7, v90
	v_mul_f32_e32 v10, v10, v90
	v_mul_f32_e32 v11, v14, v20
	v_mul_f32_e32 v14, v15, v21
	v_med3_f32 v15, v7, s62, v89
	v_med3_f32 v10, v10, s62, v89
	v_mov_b32_e32 v7, v69
	v_cvt_pk_fp8_f32 v7, v15, v10
	v_mul_f32_e32 v11, v11, v90
	v_mul_f32_e32 v10, v14, v90
	v_med3_f32 v11, v11, s62, v89
	v_med3_f32 v10, v10, s62, v89
	v_cvt_pk_fp8_f32 v7, v11, v10 op_sel:[0,0,1]
	v_mul_f32_e32 v10, v78, v26
	v_mul_f32_e32 v11, v79, v27
	v_lshl_add_u64 v[2:3], s[24:25], 0, v[2:3]
	v_mul_f32_e32 v10, v10, v90
	v_mul_f32_e32 v11, v11, v90
	v_lshl_add_u64 v[2:3], v[2:3], 0, s[52:53]
	v_med3_f32 v58, v10, s62, v89
	v_med3_f32 v11, v11, s62, v89
	v_mov_b32_e32 v10, v69
	v_mul_f32_e32 v4, v4, v26
	v_mul_f32_e32 v5, v5, v27
	v_cvt_pk_fp8_f32 v10, v58, v11
	v_lshl_add_u64 v[2:3], v[2:3], 0, v[164:165]
	v_mul_f32_e32 v4, v4, v90
	v_mul_f32_e32 v5, v5, v90
	v_mul_f32_e32 v14, v80, v28
	v_mul_f32_e32 v15, v81, v29
	global_store_dwordx2 v[2:3], v[6:7], off
	v_mul_f32_e32 v6, v8, v28
	v_med3_f32 v8, v4, s62, v89
	v_med3_f32 v5, v5, s62, v89
	v_mov_b32_e32 v4, v69
	v_mul_f32_e32 v14, v14, v90
	v_mul_f32_e32 v11, v15, v90
	v_cvt_pk_fp8_f32 v4, v8, v5
	v_med3_f32 v14, v14, s62, v89
	v_med3_f32 v11, v11, s62, v89
	v_mul_f32_e32 v7, v9, v29
	v_cvt_pk_fp8_f32 v10, v14, v11 op_sel:[0,0,1]
	v_mul_f32_e32 v11, v82, v18
	v_mul_f32_e32 v14, v83, v19
	v_mul_f32_e32 v6, v6, v90
	v_mul_f32_e32 v5, v7, v90
	v_mul_f32_e32 v11, v11, v90
	v_mul_f32_e32 v14, v14, v90
	v_med3_f32 v6, v6, s62, v89
	v_med3_f32 v5, v5, s62, v89
	v_med3_f32 v78, v11, s62, v89
	v_med3_f32 v14, v14, s62, v89
	v_mov_b32_e32 v11, v69
	v_cvt_pk_fp8_f32 v4, v6, v5 op_sel:[0,0,1]
	v_mul_f32_e32 v5, v12, v18
	v_mul_f32_e32 v6, v13, v19
	v_cvt_pk_fp8_f32 v11, v78, v14
	v_mul_f32_e32 v5, v5, v90
	v_mul_f32_e32 v6, v6, v90
	v_mul_f32_e32 v15, v84, v20
	v_mul_f32_e32 v58, v85, v21
	v_med3_f32 v9, v5, s62, v89
	v_med3_f32 v6, v6, s62, v89
	v_mov_b32_e32 v5, v69
	v_mul_f32_e32 v15, v15, v90
	v_mul_f32_e32 v14, v58, v90
	v_cvt_pk_fp8_f32 v5, v9, v6
	v_med3_f32 v15, v15, s62, v89
	v_med3_f32 v14, v14, s62, v89
	v_mul_f32_e32 v7, v16, v20
	v_mul_f32_e32 v8, v17, v21
	v_cvt_pk_fp8_f32 v11, v15, v14 op_sel:[0,0,1]
	v_mul_f32_e32 v7, v7, v90
	v_mul_f32_e32 v6, v8, v90
	v_med3_f32 v7, v7, s62, v89
	v_med3_f32 v6, v6, s62, v89
	v_cvt_pk_fp8_f32 v5, v7, v6 op_sel:[0,0,1]
	v_mul_f32_e32 v6, v70, v26
	v_mul_f32_e32 v7, v71, v27
	v_lshl_add_u64 v[2:3], v[2:3], 0, s[4:5]
	v_mul_f32_e32 v6, v6, v90
	v_mul_f32_e32 v7, v7, v90
	global_store_dwordx2 v[2:3], v[10:11], off
	v_med3_f32 v10, v6, s62, v89
	v_med3_f32 v7, v7, s62, v89
	v_mov_b32_e32 v6, v69
	v_cvt_pk_fp8_f32 v6, v10, v7
	v_mul_f32_e32 v8, v72, v28
	v_mul_f32_e32 v9, v73, v29
	v_mul_f32_e32 v8, v8, v90
	v_mul_f32_e32 v7, v9, v90
	v_med3_f32 v8, v8, s62, v89
	v_med3_f32 v7, v7, s62, v89
	v_cvt_pk_fp8_f32 v6, v8, v7 op_sel:[0,0,1]
	v_mul_f32_e32 v7, v74, v18
	v_mul_f32_e32 v8, v75, v19
	v_mul_f32_e32 v7, v7, v90
	v_mul_f32_e32 v8, v8, v90
	v_med3_f32 v11, v7, s62, v89
	v_med3_f32 v8, v8, s62, v89
	v_mov_b32_e32 v7, v69
	v_cvt_pk_fp8_f32 v7, v11, v8
	v_mul_f32_e32 v9, v76, v20
	v_mul_f32_e32 v10, v77, v21
	v_mul_f32_e32 v9, v9, v90
	v_mul_f32_e32 v8, v10, v90
	v_med3_f32 v9, v9, s62, v89
	v_med3_f32 v8, v8, s62, v89
	v_cvt_pk_fp8_f32 v7, v9, v8 op_sel:[0,0,1]
	v_lshl_add_u64 v[2:3], v[2:3], 0, s[4:5]
	global_store_dwordx2 v[2:3], v[4:5], off
	v_lshl_add_u64 v[2:3], v[2:3], 0, s[4:5]
	global_store_dwordx2 v[2:3], v[6:7], off
	s_branch .LBB0_1983

.LBB0_2203:
	s_mov_b32 s69, 0
	s_mov_b32 s68, s63
	s_waitcnt vmcnt(0)
	s_branch .LBB0_2205
.LBB0_2204:
	s_waitcnt vmcnt(0)
	s_andn2_b64 vcc, exec, s[54:55]
	s_mov_b64 s[24:25], s[52:53]
	s_mov_b32 s8, s66
	s_mov_b32 s33, s67
	s_mov_b32 s50, s56
	v_mov_b32_e32 v90, v92
	v_mov_b32_e32 v2, v54
	v_mov_b32_e32 v78, v55
	v_mov_b32_e32 v4, v56
	v_mov_b32_e32 v70, v57
	v_mov_b32_e32 v58, v50
	v_mov_b32_e32 v79, v51
	v_mov_b32_e32 v5, v52
	v_mov_b32_e32 v71, v53
	v_mov_b32_e32 v6, v42
	v_mov_b32_e32 v80, v43
	v_mov_b32_e32 v8, v44
	v_mov_b32_e32 v72, v45
	v_mov_b32_e32 v7, v38
	v_mov_b32_e32 v81, v39
	v_mov_b32_e32 v9, v40
	v_mov_b32_e32 v73, v41
	v_mov_b32_e32 v10, v34
	v_mov_b32_e32 v82, v35
	v_mov_b32_e32 v12, v36
	v_mov_b32_e32 v74, v37
	v_mov_b32_e32 v11, v30
	v_mov_b32_e32 v83, v31
	v_mov_b32_e32 v13, v32
	v_mov_b32_e32 v75, v33
	v_mov_b32_e32 v14, v22
	v_mov_b32_e32 v84, v23
	v_mov_b32_e32 v16, v24
	v_mov_b32_e32 v76, v25
	s_waitcnt vmcnt(0)
	v_mov_b32_e32 v15, v46
	v_mov_b32_e32 v85, v47
	v_mov_b32_e32 v17, v48
	v_mov_b32_e32 v77, v49
	v_mov_b32_e32 v26, v60
	v_mov_b32_e32 v27, v61
	v_mov_b32_e32 v28, v62
	v_mov_b32_e32 v29, v63
	v_mov_b32_e32 v18, v64
	v_mov_b32_e32 v19, v65
	v_mov_b32_e32 v20, v66
	v_mov_b32_e32 v21, v67
	s_cbranch_vccz .LBB0_2179

.LBB0_2269:
	v_mul_f32_e32 v93, v2, v26
	v_add_u32_e32 v2, s33, v1
	v_ashrrev_i32_e32 v95, 31, v2
	v_mad_u64_u32 v[2:3], s[36:37], v2, s8, 0
	v_mov_b32_e32 v94, v3
	v_cmp_nlt_f32_e32 vcc, 0, v90
	v_mad_u64_u32 v[94:95], s[36:37], v95, s8, v[94:95]
	v_mov_b32_e32 v3, v94
	s_ashr_i32 s51, s50, 31
	s_mov_b64 s[36:37], -1
	v_mul_f32_e32 v58, v58, v27
	s_cbranch_vccz .LBB0_2271
	v_lshl_add_u64 v[94:95], v[2:3], 1, s[24:25]
	v_lshl_add_u64 v[94:95], s[50:51], 1, v[94:95]
	v_lshlrev_b32_e32 v96, 1, v164
	v_mov_b32_e32 v97, v69
	v_lshl_add_u64 v[98:99], v[94:95], 0, v[96:97]
	v_pk_mul_f32 v[96:97], v[6:7], v[28:29]
	v_pk_mul_f32 v[100:101], v[14:15], v[20:21]
	v_cvt_pk_bf16_f32 v95, v96, v97
	v_pk_mul_f32 v[96:97], v[10:11], v[18:19]
	v_cvt_pk_bf16_f32 v94, v93, v58
	v_cvt_pk_bf16_f32 v96, v96, v97
	v_cvt_pk_bf16_f32 v97, v100, v101
	global_store_dwordx4 v[98:99], v[94:97], off
	v_pk_mul_f32 v[100:101], v[84:85], v[20:21]
	s_lshl_b64 s[36:37], s[8:9], 1
	v_pk_mul_f32 v[94:95], v[78:79], v[26:27]
	v_pk_mul_f32 v[96:97], v[80:81], v[28:29]
	v_cvt_pk_bf16_f32 v94, v94, v95
	v_cvt_pk_bf16_f32 v95, v96, v97
	v_pk_mul_f32 v[96:97], v[82:83], v[18:19]
	v_lshl_add_u64 v[98:99], v[98:99], 0, s[36:37]
	v_cvt_pk_bf16_f32 v96, v96, v97
	v_cvt_pk_bf16_f32 v97, v100, v101
	global_store_dwordx4 v[98:99], v[94:97], off
	v_pk_mul_f32 v[100:101], v[16:17], v[20:21]
	v_lshl_add_u64 v[98:99], v[98:99], 0, s[36:37]
	v_pk_mul_f32 v[94:95], v[4:5], v[26:27]
	v_pk_mul_f32 v[96:97], v[8:9], v[28:29]
	v_cvt_pk_bf16_f32 v94, v94, v95
	v_cvt_pk_bf16_f32 v95, v96, v97
	v_pk_mul_f32 v[96:97], v[12:13], v[18:19]
	s_nop 0
	v_cvt_pk_bf16_f32 v96, v96, v97
	v_cvt_pk_bf16_f32 v97, v100, v101
	global_store_dwordx4 v[98:99], v[94:97], off
	v_pk_mul_f32 v[100:101], v[76:77], v[20:21]
	v_lshl_add_u64 v[98:99], v[98:99], 0, s[36:37]
	v_pk_mul_f32 v[94:95], v[70:71], v[26:27]
	v_pk_mul_f32 v[96:97], v[72:73], v[28:29]
	v_cvt_pk_bf16_f32 v94, v94, v95
	v_cvt_pk_bf16_f32 v95, v96, v97
	v_pk_mul_f32 v[96:97], v[74:75], v[18:19]
	s_mov_b64 s[36:37], 0
	v_cvt_pk_bf16_f32 v96, v96, v97
	v_cvt_pk_bf16_f32 v97, v100, v101
	global_store_dwordx4 v[98:99], v[94:97], off
.LBB0_2271:
	s_andn2_b64 vcc, exec, s[36:37]
	s_cbranch_vccnz .LBB0_2204
	v_mul_f32_e32 v93, v93, v90
	v_mul_f32_e32 v58, v58, v90
	v_mul_f32_e32 v6, v6, v28
	v_mul_f32_e32 v94, v6, v90
	v_med3_f32 v93, v93, s61, v89
	v_med3_f32 v58, v58, s61, v89
	v_mov_b32_e32 v6, v69
	v_cvt_pk_fp8_f32 v6, v93, v58
	v_mul_f32_e32 v7, v7, v29
	v_mul_f32_e32 v7, v7, v90
	v_med3_f32 v58, v94, s61, v89
	v_med3_f32 v7, v7, s61, v89
	v_cvt_pk_fp8_f32 v6, v58, v7 op_sel:[0,0,1]
	v_mul_f32_e32 v7, v10, v18
	v_mul_f32_e32 v10, v11, v19
	v_mul_f32_e32 v7, v7, v90
	v_mul_f32_e32 v10, v10, v90
	v_mul_f32_e32 v11, v14, v20
	v_mul_f32_e32 v14, v15, v21
	v_med3_f32 v15, v7, s61, v89
	v_med3_f32 v10, v10, s61, v89
	v_mov_b32_e32 v7, v69
	v_cvt_pk_fp8_f32 v7, v15, v10
	v_mul_f32_e32 v11, v11, v90
	v_mul_f32_e32 v10, v14, v90
	v_med3_f32 v11, v11, s61, v89
	v_med3_f32 v10, v10, s61, v89
	v_cvt_pk_fp8_f32 v7, v11, v10 op_sel:[0,0,1]
	v_mul_f32_e32 v10, v78, v26
	v_mul_f32_e32 v11, v79, v27
	v_lshl_add_u64 v[2:3], s[24:25], 0, v[2:3]
	v_mul_f32_e32 v10, v10, v90
	v_mul_f32_e32 v11, v11, v90
	v_lshl_add_u64 v[2:3], v[2:3], 0, s[50:51]
	v_med3_f32 v58, v10, s61, v89
	v_med3_f32 v11, v11, s61, v89
	v_mov_b32_e32 v10, v69
	v_mul_f32_e32 v4, v4, v26
	v_mul_f32_e32 v5, v5, v27
	v_cvt_pk_fp8_f32 v10, v58, v11
	v_lshl_add_u64 v[2:3], v[2:3], 0, v[164:165]
	v_mul_f32_e32 v4, v4, v90
	v_mul_f32_e32 v5, v5, v90
	v_mul_f32_e32 v14, v80, v28
	v_mul_f32_e32 v15, v81, v29
	global_store_dwordx2 v[2:3], v[6:7], off
	v_mul_f32_e32 v6, v8, v28
	v_med3_f32 v8, v4, s61, v89
	v_med3_f32 v5, v5, s61, v89
	v_mov_b32_e32 v4, v69
	v_mul_f32_e32 v14, v14, v90
	v_mul_f32_e32 v11, v15, v90
	v_cvt_pk_fp8_f32 v4, v8, v5
	v_med3_f32 v14, v14, s61, v89
	v_med3_f32 v11, v11, s61, v89
	v_mul_f32_e32 v7, v9, v29
	v_cvt_pk_fp8_f32 v10, v14, v11 op_sel:[0,0,1]
	v_mul_f32_e32 v11, v82, v18
	v_mul_f32_e32 v14, v83, v19
	v_mul_f32_e32 v6, v6, v90
	v_mul_f32_e32 v5, v7, v90
	v_mul_f32_e32 v11, v11, v90
	v_mul_f32_e32 v14, v14, v90
	v_med3_f32 v6, v6, s61, v89
	v_med3_f32 v5, v5, s61, v89
	v_med3_f32 v78, v11, s61, v89
	v_med3_f32 v14, v14, s61, v89
	v_mov_b32_e32 v11, v69
	v_cvt_pk_fp8_f32 v4, v6, v5 op_sel:[0,0,1]
	v_mul_f32_e32 v5, v12, v18
	v_mul_f32_e32 v6, v13, v19
	v_cvt_pk_fp8_f32 v11, v78, v14
	v_mul_f32_e32 v5, v5, v90
	v_mul_f32_e32 v6, v6, v90
	v_mul_f32_e32 v15, v84, v20
	v_mul_f32_e32 v58, v85, v21
	v_med3_f32 v9, v5, s61, v89
	v_med3_f32 v6, v6, s61, v89
	v_mov_b32_e32 v5, v69
	v_mul_f32_e32 v15, v15, v90
	v_mul_f32_e32 v14, v58, v90
	v_cvt_pk_fp8_f32 v5, v9, v6
	v_med3_f32 v15, v15, s61, v89
	v_med3_f32 v14, v14, s61, v89
	v_mul_f32_e32 v7, v16, v20
	v_mul_f32_e32 v8, v17, v21
	v_cvt_pk_fp8_f32 v11, v15, v14 op_sel:[0,0,1]
	v_mul_f32_e32 v7, v7, v90
	v_mul_f32_e32 v6, v8, v90
	v_med3_f32 v7, v7, s61, v89
	v_med3_f32 v6, v6, s61, v89
	v_cvt_pk_fp8_f32 v5, v7, v6 op_sel:[0,0,1]
	v_mul_f32_e32 v6, v70, v26
	v_mul_f32_e32 v7, v71, v27
	v_lshl_add_u64 v[2:3], v[2:3], 0, s[8:9]
	v_mul_f32_e32 v6, v6, v90
	v_mul_f32_e32 v7, v7, v90
	global_store_dwordx2 v[2:3], v[10:11], off
	v_med3_f32 v10, v6, s61, v89
	v_med3_f32 v7, v7, s61, v89
	v_mov_b32_e32 v6, v69
	v_cvt_pk_fp8_f32 v6, v10, v7
	v_mul_f32_e32 v8, v72, v28
	v_mul_f32_e32 v9, v73, v29
	v_mul_f32_e32 v8, v8, v90
	v_mul_f32_e32 v7, v9, v90
	v_med3_f32 v8, v8, s61, v89
	v_med3_f32 v7, v7, s61, v89
	v_cvt_pk_fp8_f32 v6, v8, v7 op_sel:[0,0,1]
	v_mul_f32_e32 v7, v74, v18
	v_mul_f32_e32 v8, v75, v19
	v_mul_f32_e32 v7, v7, v90
	v_mul_f32_e32 v8, v8, v90
	v_med3_f32 v11, v7, s61, v89
	v_med3_f32 v8, v8, s61, v89
	v_mov_b32_e32 v7, v69
	v_cvt_pk_fp8_f32 v7, v11, v8
	v_mul_f32_e32 v9, v76, v20
	v_mul_f32_e32 v10, v77, v21
	v_mul_f32_e32 v9, v9, v90
	v_mul_f32_e32 v8, v10, v90
	v_med3_f32 v9, v9, s61, v89
	v_med3_f32 v8, v8, s61, v89
	v_cvt_pk_fp8_f32 v7, v9, v8 op_sel:[0,0,1]
	v_lshl_add_u64 v[2:3], v[2:3], 0, s[8:9]
	global_store_dwordx2 v[2:3], v[4:5], off
	v_lshl_add_u64 v[2:3], v[2:3], 0, s[8:9]
	global_store_dwordx2 v[2:3], v[6:7], off
	s_branch .LBB0_2204
